# v18 + in-XCD stagger of residual GEMM phases G2/G4: blocks >=128 (second tile group of each XCD) start 3x s_sleep127 late so RMW epilogue bursts of the two groups do not coincide
# speedup vs baseline: 1.0086x; 1.0086x over previous
; #define PG8_WAIT_V(n) asm volatile("s_waitcnt vmcnt(" #n ")" ::: "memory")
; template <class Epi, class Sched, bool ALIGN_EPI = false, bool SP2 = false>
; __device__ __forceinline__ void gemm_phase(PG8_LAS unsigned char* lds, const Gemm g, const Sched& S, const Epi& E) {
;     int tid_o = threadIdx.x; asm volatile("" : "+v"(tid_o));
;     const int tid = tid_o, wid = __builtin_amdgcn_readfirstlane(tid >> 6), lane = tid & 63, wr = wid >> 2, wc = wid & 3, fr = lane & 15, fq = lane >> 4;
;     const int K = g.K, nt = K / BK;
;     unsigned voffA[2], voffB[2];
; #pragma unroll
;     for (int i = 0; i < 2; ++i) { int R, C; stage_rc(tid * 16 + i * 8192, R, C); const int Rb = Epi::PERM ? ((R & ~31) + perm32(R & 31)) : R;
;         voffA[i] = (unsigned)(R * K + C) * 2u; voffB[i] = (unsigned)(Rb * K + C) * 2u; }
;     const size_t kstep = (size_t)(BK * 2);
;     const size_t hstep = (size_t)HALF * K * 2;
;     const size_t tstep = 2 * hstep;
;     const unsigned ldsw = (unsigned)wid * 1024u;
;     const int aoff = lds_byte(wr * 64 + fr, fq * 8), boff = lds_byte(wc * 32 + fr, fq * 8);
;     ...
;     Unit cur, nxt; int ui = 0;
;     if (!S.next(0, cur)) return;
;     f32x4 acc[2][2][4][2];
; #pragma unroll
;     for (int a = 0; a < 2; ++a)
; #pragma unroll
;         for (int b = 0; b < 2; ++b)
; #pragma unroll
;             for (int m = 0; m < 4; ++m)
; #pragma unroll
;                 for (int n = 0; n < 2; ++n) acc[a][b][m][n] = (f32x4){0.f, 0.f, 0.f, 0.f};
;     bf16x8 At[4][2], B0[2][2], B1[2][2];
;     const char* cA = (const char*)g.A + (size_t)cur.pm * tstep; const char* cB = (const char*)g.Bt + (size_t)cur.pn * tstep;
;     S.a_ready(cur);
;     if constexpr (SP2) {
;         PG8_STAGE(PG8_SB(0, 0), cB, voffB); PG8_STAGE(PG8_SB(0, 1), cB + hstep, voffB); PG8_STAGE(PG8_SA(0, 0), cA, voffA); PG8_STAGE(PG8_SA(0, 1), cA + hstep, voffA);
;         if (wr == 1) PG8_BAR;
;         PG8_WAIT_V(2); PG8_BAR;
; __global__ void __launch_bounds__(512, 2) hybrid_fwd(Params Parg) {
;     ...
;         { const Params P = fresh_params(); const int G = gridDim.x, blk = blockIdx.x;
;           const float* modl = (const float*)(P.ws + WS_MOD) + (size_t)l * 17 * MODW;
;           pg8::Gemm g{(const pg8::bf16_t*)(P.ws + WS_H), (const pg8::bf16_t*)(P.ws + (size_t)(l & 1) * WS_WBUF + WS_W_OUT), ROWS, DM, DM};
;           EpiResid E{P.out, (float*)(P.ws + WS_XC), modl + 2 * DM};
.LBB0_838:
	s_or_b64 exec, exec, s[0:1]
	s_mov_b64 s[0:1], s[28:29]
	s_waitcnt lgkmcnt(0)
	s_barrier
	s_load_dwordx4 s[44:47], s[0:1], 0x98
	s_mul_i32 s64, s6, 0x19800
	s_lshl_b64 s[6:7], s[64:65], 2
	v_readlane_b32 s12, v253, 52
	v_readlane_b32 s13, v253, 53
	s_waitcnt lgkmcnt(0)
	s_add_u32 s0, s46, s6
	v_writelane_b32 v255, s6, 30
	s_addc_u32 s1, s47, s7
	s_add_u32 s8, s46, 0x5500000
	s_addc_u32 s9, s47, 0
	s_add_u32 s10, s46, s70
	s_addc_u32 s11, s47, 0
	s_add_u32 s28, s10, 0x980000
	s_addc_u32 s29, s11, 0
	v_writelane_b32 v255, s7, 31
	s_add_u32 s64, s46, 0x4500000
	s_addc_u32 s40, s47, 0
	v_readlane_b32 s6, v255, 3
	s_add_u32 s41, s0, 0x102000
	v_readlane_b32 s7, v255, 4
	v_cndmask_b32_e64 v0, 0, 1, s[12:13]
	s_addc_u32 s0, s1, 0
	s_and_b64 vcc, exec, s[6:7]
	v_cmp_ne_u32_e64 s[6:7], 1, v0
	s_mov_b64 s[10:11], -1
	s_nop 0
	v_writelane_b32 v255, s6, 32
	s_nop 1
	v_writelane_b32 v255, s7, 33
	s_cbranch_vccz .LBB0_860
	s_cmp_lt_u32 s2, 128
	s_cbranch_scc1 .Lg2gs_go
	s_mov_b32 s100, 3
.Lg2gs_dl:
	s_sleep 127
	s_sub_u32 s100, s100, 1
	s_cmp_lg_u32 s100, 0
	s_cbranch_scc1 .Lg2gs_dl
.Lg2gs_go:
	v_readlane_b32 s6, v255, 32
	v_mov_b32_e32 v12, v200
	v_readlane_b32 s7, v255, 33
	s_and_b64 vcc, exec, s[6:7]
	v_readfirstlane_b32 s12, v12
	s_cbranch_vccnz .LBB0_859
	v_lshlrev_b32_e32 v0, 4, v12
	v_add_u32_e32 v1, 0x2000, v0
	v_ashrrev_i32_e32 v2, 31, v1
	v_lshrrev_b32_e32 v2, 22, v2
	v_add_u32_e32 v2, v1, v2
	s_waitcnt vmcnt(2)
	v_ashrrev_i32_e32 v8, 10, v2
	v_mul_i32_i24_e32 v2, 0x400, v8
	v_sub_u32_e32 v1, v1, v2
	v_lshrrev_b32_e32 v2, 4, v1
	v_bitop3_b32 v1, v2, v1, 32 bitop3:0x6c
	v_ashrrev_i32_e32 v2, 31, v1
	v_lshrrev_b32_e32 v2, 26, v2
	v_add_u32_e32 v2, v1, v2
	v_ashrrev_i32_e32 v9, 6, v2
	v_and_b32_e32 v2, 0xc0, v2
	v_sub_u32_e32 v1, v1, v2
	v_ashrrev_i16_sdwa v1, v203, sext(v1) dst_sel:DWORD dst_unused:UNUSED_PAD src0_sel:DWORD src1_sel:BYTE_0
	v_bfe_i32 v11, v1, 0, 16
	v_bfe_i32 v1, v12, 27, 1
	v_lshrrev_b32_e32 v1, 22, v1
	v_add_u32_e32 v1, v0, v1
	v_and_b32_e32 v1, 0xfffffc00, v1
	v_sub_u32_e32 v0, v0, v1
	v_lshrrev_b32_e32 v1, 4, v0
	v_bitop3_b32 v0, v1, v0, 32 bitop3:0x6c
	v_ashrrev_i32_e32 v2, 31, v12
	v_lshlrev_b32_e32 v3, 3, v8
	v_ashrrev_i32_e32 v1, 31, v0
	v_lshrrev_b32_e32 v2, 26, v2
	v_and_b32_e32 v3, 0x1ffff0, v3
	v_lshlrev_b32_e32 v4, 5, v8
	v_lshrrev_b32_e32 v1, 26, v1
	v_add_u32_e32 v2, v12, v2
	v_add_u32_e32 v3, v9, v3
	v_and_b32_e32 v10, 32, v4
	v_add_u32_e32 v1, v0, v1
	v_ashrrev_i32_e32 v14, 6, v2
	s_ashr_i32 s15, s12, 6
	v_lshl_or_b32 v3, v3, 10, v10
	v_ashrrev_i32_e32 v13, 6, v1
	v_lshlrev_b32_e32 v2, 3, v14
	v_and_b32_e32 v1, 0xc0, v1
	s_ashr_i32 s13, s12, 8
	s_lshl_b32 s1, s15, 10
	v_add_lshl_u32 v146, v3, v11, 1
	v_and_b32_e32 v2, 0x1ffff0, v2
	v_lshlrev_b32_e32 v3, 5, v14
	v_sub_u32_e32 v0, v0, v1
	v_readlane_b32 s10, v254, 5
	v_add_u32_e32 v2, v13, v2
	v_and_b32_e32 v15, 32, v3
	v_ashrrev_i16_sdwa v0, v203, sext(v0) dst_sel:DWORD dst_unused:UNUSED_PAD src0_sel:DWORD src1_sel:BYTE_0
	v_readlane_b32 s11, v254, 6
	s_add_u32 s52, s28, s10
	v_lshl_or_b32 v2, v2, 10, v15
	v_bfe_i32 v16, v0, 0, 16
	s_addc_u32 s53, s29, s11
	s_add_i32 s58, s1, 0
	v_add_lshl_u32 v128, v2, v16, 1
	s_add_i32 m0, s58, 0x10000
	v_readlane_b32 s6, v254, 33
	global_load_lds_dwordx4 v128, s[52:53]
	s_add_i32 m0, s58, 0x12000
	s_add_u32 s10, s52, 0x40000
	global_load_lds_dwordx4 v146, s[52:53]
	s_addc_u32 s11, s53, 0
	s_add_i32 m0, s58, 0x14000
	v_readlane_b32 s7, v254, 34
	global_load_lds_dwordx4 v128, s[10:11]
	s_add_i32 m0, s58, 0x16000
	s_add_u32 s50, s8, s6
	s_addc_u32 s51, s9, s7
	s_add_i32 s18, s58, 0x2000
	global_load_lds_dwordx4 v146, s[10:11]
	s_mov_b32 m0, s58
	s_add_u32 s10, s50, 0x40000
	global_load_lds_dwordx4 v128, s[50:51]
	s_mov_b32 m0, s18
	s_addc_u32 s11, s51, 0
	s_add_i32 s19, s58, 0x4000
	global_load_lds_dwordx4 v146, s[50:51]
	s_mov_b32 m0, s19
	s_add_i32 s59, s58, 0x6000
	global_load_lds_dwordx4 v128, s[10:11]
	s_mov_b32 m0, s59
	v_mov_b32_e32 v147, v129
	global_load_lds_dwordx4 v146, s[10:11]
	s_cmp_eq_u32 s13, 1
	v_lshl_add_u64 v[6:7], s[52:53], 0, v[128:129]
	v_lshl_add_u64 v[4:5], s[52:53], 0, v[146:147]
	v_lshl_add_u64 v[0:1], s[50:51], 0, v[128:129]
	s_cselect_b64 s[10:11], -1, 0
	s_cmp_lg_u32 s13, 1
	v_lshl_add_u64 v[2:3], s[50:51], 0, v[146:147]
	s_cbranch_scc1 .LBB0_842
	s_barrier

;     __device__ void init(int N, int G, int c) { S.init(NBATCH * SEQ, N, G, c); }
;     __device__ __forceinline__ void operator()(const pg8::f32x4 (&acc)[2][2][4][2], const pg8::Unit& u, int wr, int wc, int fr, int fq) const {
;         const int b = u.pm / 9, j = u.pm - b * 9;
;         float* base = (j == 0) ? xc + (size_t)b * CTX * DM : out + ((size_t)b * SEQ + (size_t)(j - 1) * 256) * DM;
;         const float* g = gate + (size_t)((j == 0) ? 16 : b) * MODW;
; __global__ void __launch_bounds__(512, 2) hybrid_fwd(Params Parg) {
;     ...
;         { const Params P = fresh_params(); const int G = gridDim.x, blk = blockIdx.x;
;           const float* modl = (const float*)(P.ws + WS_MOD) + (size_t)l * 17 * MODW;
;           pg8::Gemm g{(const pg8::bf16_t*)(P.ws + WS_PROJ), (const pg8::bf16_t*)(P.ws + (size_t)(l & 1) * WS_WBUF + WS_W_FO), ROWS, DM, FFH};
;           EpiResid E{P.out, (float*)(P.ws + WS_XC), modl + 5 * DM};
;           if (lat_only) { LatOrder S; S.init(DM, G, blk); pg8::gemm_phase<EpiResid, LatOrder, RES_ALIGN, true>(ldsl, g, S, E); }
;           else { pg8::StaticOrder S; S.init(ROWS, DM, G, blk); pg8::gemm_phase<EpiResid, pg8::StaticOrder, RES_ALIGN, true>(ldsl, g, S, E); }
.LBB0_1079:
	s_mov_b32 s12, s70
	s_movk_i32 s70, 0xf700
	s_mov_b32 s6, 0x38e38e39
	s_or_b64 exec, exec, s[10:11]
	s_mov_b64 s[0:1], s[18:19]
	s_waitcnt lgkmcnt(0)
	s_barrier
	s_load_dwordx4 s[52:55], s[0:1], 0x98
	s_load_dwordx4 s[40:43], s[0:1], 0x80
	s_load_dwordx2 s[34:35], s[0:1], 0x38
	s_load_dwordx2 s[36:37], s[0:1], 0x70
	v_readlane_b32 s0, v255, 30
	v_readlane_b32 s1, v255, 31
	s_waitcnt lgkmcnt(0)
	s_add_u32 s0, s54, s0
	s_addc_u32 s1, s55, s1
	s_add_u32 s8, s54, 0x9d00000
	s_addc_u32 s9, s55, 0
	s_add_u32 s10, s54, s12
	s_addc_u32 s11, s55, 0
	s_add_u32 s28, s10, 0x1680000
	s_addc_u32 s29, s11, 0
	s_add_u32 s64, s54, 0x4500000
	s_addc_u32 s10, s55, 0
	v_readlane_b32 s12, v255, 3
	s_add_u32 s11, s0, 0x105000
	v_readlane_b32 s13, v255, 4
	s_addc_u32 s24, s1, 0
	s_mov_b64 s[0:1], -1
	s_and_b64 vcc, exec, s[12:13]
	s_cbranch_vccz .LBB0_1105
	s_cmp_lt_u32 s2, 128
	s_cbranch_scc1 .Lg4gs_go
	s_mov_b32 s100, 3

; #define PG8_STAGE(bufoff, gbase, voff) do { _Pragma("unroll") for (int _i = 0; _i < 2; ++_i) \
;         __builtin_amdgcn_global_load_lds((const unsigned*)((const char*)(gbase) + (voff)[_i]), (PG8_LAS unsigned*)(lds + (bufoff) + ldsw + _i * 8192), 16, 0, 0); } while (0)
; #define PG8_WAIT_V(n) asm volatile("s_waitcnt vmcnt(" #n ")" ::: "memory")
; #define PG8_BAR __builtin_amdgcn_s_barrier()
;     __device__ bool next(int i, pg8::Unit& u) const { if (i != 0) return false; u.pm = pm; u.pn = pn; return true; }
; template <class Epi, class Sched, bool ALIGN_EPI = false, bool SP2 = false>
; __device__ __forceinline__ void gemm_phase(PG8_LAS unsigned char* lds, const Gemm g, const Sched& S, const Epi& E) {
;     int tid_o = threadIdx.x; asm volatile("" : "+v"(tid_o));
;     const int tid = tid_o, wid = __builtin_amdgcn_readfirstlane(tid >> 6), lane = tid & 63, wr = wid >> 2, wc = wid & 3, fr = lane & 15, fq = lane >> 4;
;     const int K = g.K, nt = K / BK;
;     unsigned voffA[2], voffB[2];
; #pragma unroll
;     for (int i = 0; i < 2; ++i) { int R, C; stage_rc(tid * 16 + i * 8192, R, C); const int Rb = Epi::PERM ? ((R & ~31) + perm32(R & 31)) : R;
;         voffA[i] = (unsigned)(R * K + C) * 2u; voffB[i] = (unsigned)(Rb * K + C) * 2u; }
;     const size_t kstep = (size_t)(BK * 2);
;     const size_t hstep = (size_t)HALF * K * 2;
;     const size_t tstep = 2 * hstep;
;     const unsigned ldsw = (unsigned)wid * 1024u;
;     const int aoff = lds_byte(wr * 64 + fr, fq * 8), boff = lds_byte(wc * 32 + fr, fq * 8);
;     ...
;     Unit cur, nxt; int ui = 0;
;     if (!S.next(0, cur)) return;
;     f32x4 acc[2][2][4][2];
; #pragma unroll
;     for (int a = 0; a < 2; ++a)
; #pragma unroll
;         for (int b = 0; b < 2; ++b)
; #pragma unroll
;             for (int m = 0; m < 4; ++m)
; #pragma unroll
;                 for (int n = 0; n < 2; ++n) acc[a][b][m][n] = (f32x4){0.f, 0.f, 0.f, 0.f};
;     bf16x8 At[4][2], B0[2][2], B1[2][2];
;     const char* cA = (const char*)g.A + (size_t)cur.pm * tstep; const char* cB = (const char*)g.Bt + (size_t)cur.pn * tstep;
;     S.a_ready(cur);
;     if constexpr (SP2) {
;         PG8_STAGE(PG8_SB(0, 0), cB, voffB); PG8_STAGE(PG8_SB(0, 1), cB + hstep, voffB); PG8_STAGE(PG8_SA(0, 0), cA, voffA); PG8_STAGE(PG8_SA(0, 1), cA + hstep, voffA);
;         if (wr == 1) PG8_BAR;
;         PG8_WAIT_V(2); PG8_BAR;
.Lg4gs_go:
	v_readlane_b32 s0, v255, 32
	v_mov_b32_e32 v12, v200
	v_readlane_b32 s1, v255, 33
	s_and_b64 vcc, exec, s[0:1]
	v_readfirstlane_b32 s12, v12
	s_cbranch_vccnz .LBB0_1104
	v_lshlrev_b32_e32 v0, 4, v12
	v_add_u32_e32 v1, 0x2000, v0
	v_ashrrev_i32_e32 v2, 31, v1
	v_lshrrev_b32_e32 v2, 22, v2
	v_add_u32_e32 v2, v1, v2
	v_ashrrev_i32_e32 v8, 10, v2
	v_mul_i32_i24_e32 v2, 0x400, v8
	v_sub_u32_e32 v1, v1, v2
	v_lshrrev_b32_e32 v2, 4, v1
	v_bitop3_b32 v1, v2, v1, 32 bitop3:0x6c
	v_ashrrev_i32_e32 v2, 31, v1
	v_lshrrev_b32_e32 v2, 26, v2
	v_add_u32_e32 v2, v1, v2
	v_ashrrev_i32_e32 v9, 6, v2
	v_and_b32_e32 v2, 0xc0, v2
	v_sub_u32_e32 v1, v1, v2
	v_ashrrev_i16_sdwa v1, v203, sext(v1) dst_sel:DWORD dst_unused:UNUSED_PAD src0_sel:DWORD src1_sel:BYTE_0
	v_bfe_i32 v11, v1, 0, 16
	v_bfe_i32 v1, v12, 27, 1
	v_lshrrev_b32_e32 v1, 22, v1
	v_add_u32_e32 v1, v0, v1
	v_and_b32_e32 v1, 0xfffffc00, v1
	v_sub_u32_e32 v0, v0, v1
	v_lshrrev_b32_e32 v1, 4, v0
	v_ashrrev_i32_e32 v2, 31, v12
	v_bitop3_b32 v0, v1, v0, 32 bitop3:0x6c
	v_lshrrev_b32_e32 v2, 26, v2
	v_lshlrev_b32_e32 v3, 3, v8
	v_ashrrev_i32_e32 v1, 31, v0
	v_add_u32_e32 v2, v12, v2
	v_and_b32_e32 v3, 0xfffff0, v3
	v_lshrrev_b32_e32 v1, 26, v1
	v_ashrrev_i32_e32 v14, 6, v2
	v_add_u32_e32 v3, v9, v3
	s_movk_i32 s0, 0xb00
	v_lshlrev_b32_e32 v4, 5, v8
	v_add_u32_e32 v1, v0, v1
	v_lshlrev_b32_e32 v2, 3, v14
	v_mul_lo_u32 v3, v3, s0
	v_and_b32_e32 v10, 32, v4
	v_ashrrev_i32_e32 v13, 6, v1
	v_and_b32_e32 v2, 0xfffff0, v2
	s_ashr_i32 s15, s12, 6
	v_or_b32_e32 v3, v3, v10
	v_add_u32_e32 v2, v13, v2
	v_and_b32_e32 v1, 0xc0, v1
	v_readlane_b32 s1, v254, 4
	s_ashr_i32 s13, s12, 8
	s_lshl_b32 s25, s15, 10
	v_add_lshl_u32 v146, v3, v11, 1
	v_mul_lo_u32 v2, v2, s0
	v_lshlrev_b32_e32 v3, 5, v14
	v_sub_u32_e32 v0, v0, v1
	s_mul_i32 s0, s1, 0x160000
	v_and_b32_e32 v15, 32, v3
	v_ashrrev_i16_sdwa v0, v203, sext(v0) dst_sel:DWORD dst_unused:UNUSED_PAD src0_sel:DWORD src1_sel:BYTE_0
	s_add_u32 s56, s28, s0
	s_mul_hi_i32 s0, s1, 0x160000
	v_or_b32_e32 v2, v2, v15
	v_bfe_i32 v16, v0, 0, 16
	s_addc_u32 s57, s29, s0
	s_add_i32 s38, s25, 0
	v_add_lshl_u32 v128, v2, v16, 1
	s_add_i32 m0, s38, 0x10000
	v_writelane_b32 v255, s40, 34
	global_load_lds_dwordx4 v128, s[56:57]
	s_add_i32 m0, s38, 0x12000
	s_add_u32 s0, s56, 0xb0000
	global_load_lds_dwordx4 v146, s[56:57]
	s_addc_u32 s1, s57, 0
	s_add_i32 m0, s38, 0x14000
	v_writelane_b32 v255, s41, 35
	global_load_lds_dwordx4 v128, s[0:1]
	s_add_i32 m0, s38, 0x16000
	v_writelane_b32 v255, s42, 36
	global_load_lds_dwordx4 v146, s[0:1]
	v_readlane_b32 s0, v254, 31
	s_mov_b32 s18, s0
	s_mul_i32 s0, s0, 0x160000
	s_add_u32 s50, s8, s0
	s_mul_hi_i32 s0, s18, 0x160000
	s_addc_u32 s51, s9, s0
	s_add_i32 s18, s38, 0x2000
	v_readlane_b32 s1, v254, 32
	s_mov_b32 m0, s38
	s_add_u32 s0, s50, 0xb0000
	global_load_lds_dwordx4 v128, s[50:51]
	s_mov_b32 m0, s18
	s_addc_u32 s1, s51, 0
	s_add_i32 s19, s38, 0x4000
	global_load_lds_dwordx4 v146, s[50:51]
	s_mov_b32 m0, s19
	s_add_i32 s39, s38, 0x6000
	global_load_lds_dwordx4 v128, s[0:1]
	s_mov_b32 m0, s39
	v_writelane_b32 v255, s43, 37
	global_load_lds_dwordx4 v146, s[0:1]
	v_writelane_b32 v255, s36, 32
	v_mov_b32_e32 v147, v129
	s_cmp_eq_u32 s13, 1
	v_writelane_b32 v255, s37, 33
	v_writelane_b32 v255, s34, 30
	v_lshl_add_u64 v[6:7], s[56:57], 0, v[128:129]
	v_lshl_add_u64 v[4:5], s[56:57], 0, v[146:147]
	v_writelane_b32 v255, s35, 31
	v_lshl_add_u64 v[0:1], s[50:51], 0, v[128:129]
	s_cselect_b64 s[0:1], -1, 0
	s_cmp_lg_u32 s13, 1
	v_lshl_add_u64 v[2:3], s[50:51], 0, v[146:147]
	s_cbranch_scc1 .LBB0_1083
	s_barrier
